# version 49 + all edits that measured neutral alone (role-switch order, permlane swaps, packed row sums, attention DMA placement, spatial-gating pipelining + prefetch order, depth-2 x loop)
# baseline (speedup 1.0000x reference)
.LBB0_47:
	v_add_u32_e32 v0, s20, v224
	ds_read_b64_tr_b16 v[2:3], v0 offset:24576
	ds_read_b64_tr_b16 v[4:5], v0 offset:25088
	v_pk_add_f32 v[248:249], v[96:97], v[98:99]
	v_pk_add_f32 v[248:249], v[100:101], v[248:249]
	s_waitcnt lgkmcnt(9)
	v_mfma_f32_32x32x16_bf16 v[64:79], v[172:175], v[112:115], v[64:79]
	v_cvt_pk_bf16_f32 v140, v96, v97
	v_cvt_pk_bf16_f32 v141, v98, v99
	ds_read_b64_tr_b16 v[6:7], v0 offset:28672
	ds_read_b64_tr_b16 v[8:9], v0 offset:29184
	v_pk_add_f32 v[248:249], v[102:103], v[248:249]
	v_pk_add_f32 v[248:249], v[104:105], v[248:249]
	s_waitcnt lgkmcnt(10)
	v_mfma_f32_32x32x16_bf16 v[48:63], v[168:171], v[112:115], v[48:63]
	v_cvt_pk_bf16_f32 v142, v100, v101
	v_cvt_pk_bf16_f32 v143, v102, v103
	s_add_i32 s18, s7, s99
	v_lshl_add_u64 v[250:251], v[194:195], 0, s[24:25]
	s_mov_b32 s20, m0
	s_mov_b32 m0, s18
	s_nop 0
	global_load_lds_dwordx4 v[250:251], off
	s_mov_b32 m0, s20
	ds_read_b64_tr_b16 v[10:11], v0 offset:25600
	ds_read_b64_tr_b16 v[12:13], v0 offset:26112
	v_pk_add_f32 v[248:249], v[106:107], v[248:249]
	v_pk_add_f32 v[248:249], v[108:109], v[248:249]
	s_waitcnt lgkmcnt(11)
	v_mfma_f32_32x32x16_bf16 v[64:79], v[164:167], v[116:119], v[64:79]
	v_cvt_pk_bf16_f32 v136, v104, v105
	v_cvt_pk_bf16_f32 v137, v106, v107
	ds_read_b64_tr_b16 v[164:165], v0 offset:29696
	ds_read_b64_tr_b16 v[166:167], v0 offset:30208
	v_pk_add_f32 v[248:249], v[110:111], v[248:249]
	v_pk_add_f32 v[248:249], v[80:81], v[248:249]
	s_waitcnt lgkmcnt(12)
	v_mfma_f32_32x32x16_bf16 v[48:63], v[160:163], v[116:119], v[48:63]
	v_cvt_pk_bf16_f32 v138, v108, v109
	v_cvt_pk_bf16_f32 v139, v110, v111
	s_add_i32 s18, s29, s6
	v_lshl_add_u64 v[246:247], v[214:215], 0, s[24:25]
	s_mov_b32 s20, m0
	s_mov_b32 m0, s18
	s_nop 0
	global_load_lds_dwordx4 v[246:247], off
	s_mov_b32 m0, s20
	ds_read_b64_tr_b16 v[168:169], v0 offset:26624
	ds_read_b64_tr_b16 v[170:171], v0 offset:27136
	v_pk_add_f32 v[248:249], v[82:83], v[248:249]
	v_pk_add_f32 v[248:249], v[84:85], v[248:249]
	s_waitcnt lgkmcnt(13)
	v_mfma_f32_32x32x16_bf16 v[64:79], v[156:159], v[120:123], v[64:79]
	v_cvt_pk_bf16_f32 v132, v80, v81
	v_cvt_pk_bf16_f32 v133, v82, v83
	ds_read_b64_tr_b16 v[172:173], v0 offset:30720
	ds_read_b64_tr_b16 v[174:175], v0 offset:31232
	v_pk_add_f32 v[248:249], v[86:87], v[248:249]
	v_pk_add_f32 v[248:249], v[88:89], v[248:249]
	s_waitcnt lgkmcnt(14)
	v_mfma_f32_32x32x16_bf16 v[48:63], v[152:155], v[120:123], v[48:63]
	v_cvt_pk_bf16_f32 v134, v84, v85
	v_cvt_pk_bf16_f32 v135, v86, v87
	ds_read_b64_tr_b16 v[152:153], v0 offset:27648
	ds_read_b64_tr_b16 v[154:155], v0 offset:28160
	v_pk_add_f32 v[248:249], v[90:91], v[248:249]
	v_pk_add_f32 v[248:249], v[92:93], v[248:249]
	s_waitcnt lgkmcnt(14)
	v_mfma_f32_32x32x16_bf16 v[64:79], v[148:151], v[124:127], v[64:79]
	v_cvt_pk_bf16_f32 v128, v88, v89
	v_cvt_pk_bf16_f32 v129, v90, v91
	ds_read_b64_tr_b16 v[184:185], v0 offset:31744
	ds_read_b64_tr_b16 v[186:187], v0 offset:32256
	v_pk_add_f32 v[248:249], v[94:95], v[248:249]
	v_mfma_f32_32x32x16_bf16 v[48:63], v[144:147], v[124:127], v[48:63]
	v_add_f32_e32 v14, v248, v249
	v_cvt_pk_bf16_f32 v130, v92, v93
	v_cvt_pk_bf16_f32 v131, v94, v95
	v_add_u32_e32 v0, 0, v227
	v_add_u32_e32 v15, 0x15200, v0
	ds_read_b128 v[96:99], v15
	ds_read_b128 v[80:83], v15 offset:128
	ds_read_b128 v[100:103], v15 offset:32
	ds_read_b128 v[84:87], v15 offset:160
	ds_read_b128 v[104:107], v15 offset:64
	ds_read_b128 v[88:91], v15 offset:192
	ds_read_b128 v[108:111], v15 offset:96
	ds_read_b128 v[92:95], v15 offset:224
	s_lshl_b32 s18, 1, s44
	s_and_b32 s18, s18, s81
	s_cmp_lg_u32 s18, 0
	v_add_f32_e32 v14, v225, v14
	s_cselect_b64 s[20:21], -1, 0
	s_cmp_eq_u32 s18, 0
	s_cbranch_scc1 .LBB0_49
	s_add_i32 s18, s33, 0
	s_add_i32 s18, s18, 0x17104
	v_mov_b32_e32 v15, s18
	ds_read_b32 v212, v15
	s_waitcnt lgkmcnt(0)
	v_mul_f32_e32 v14, v14, v212

.LBB0_51:
	s_add_i32 s20, s29, 0x2000
	v_add_u32_e32 v15, s7, v224
	ds_read_b64_tr_b16 v[6:7], v15 offset:24576
	ds_read_b64_tr_b16 v[8:9], v15 offset:25088
	v_pk_add_f32 v[248:249], v[64:65], v[66:67]
	v_pk_add_f32 v[248:249], v[68:69], v[248:249]
	s_waitcnt lgkmcnt(9)
	v_mfma_f32_32x32x16_bf16 v[96:111], v[144:147], v[112:115], v[96:111]
	v_cvt_pk_bf16_f32 v140, v64, v65
	v_cvt_pk_bf16_f32 v141, v66, v67
	s_cmpk_lg_i32 s29, 0x4000
	s_cselect_b32 s7, s20, 0
	s_add_i32 s18, s29, s99
	ds_read_b64_tr_b16 v[144:145], v15 offset:28672
	ds_read_b64_tr_b16 v[146:147], v15 offset:29184
	v_pk_add_f32 v[248:249], v[70:71], v[248:249]
	v_pk_add_f32 v[248:249], v[72:73], v[248:249]
	s_waitcnt lgkmcnt(10)
	v_mfma_f32_32x32x16_bf16 v[80:95], v[180:183], v[112:115], v[80:95]
	v_cvt_pk_bf16_f32 v142, v68, v69
	v_cvt_pk_bf16_f32 v143, v70, v71
	s_mov_b32 s20, m0
	s_mov_b32 m0, s18
	s_nop 0
	global_load_lds_dwordx4 v[194:195], off
	s_mov_b32 m0, s20
	ds_read_b64_tr_b16 v[152:153], v15 offset:25600
	ds_read_b64_tr_b16 v[154:155], v15 offset:26112
	v_pk_add_f32 v[248:249], v[74:75], v[248:249]
	v_pk_add_f32 v[248:249], v[76:77], v[248:249]
	s_waitcnt lgkmcnt(11)
	v_mfma_f32_32x32x16_bf16 v[96:111], v[176:179], v[116:119], v[96:111]
	v_cvt_pk_bf16_f32 v136, v72, v73
	v_cvt_pk_bf16_f32 v137, v74, v75
	ds_read_b64_tr_b16 v[176:177], v15 offset:29696
	ds_read_b64_tr_b16 v[178:179], v15 offset:30208
	v_pk_add_f32 v[248:249], v[78:79], v[248:249]
	v_pk_add_f32 v[248:249], v[48:49], v[248:249]
	s_waitcnt lgkmcnt(12)
	v_mfma_f32_32x32x16_bf16 v[80:95], v[160:163], v[116:119], v[80:95]
	v_cvt_pk_bf16_f32 v138, v76, v77
	v_cvt_pk_bf16_f32 v139, v78, v79
	s_add_i32 s18, s7, s6
	s_mov_b32 s20, m0
	s_mov_b32 m0, s18
	s_nop 0
	global_load_lds_dwordx4 v[214:215], off
	s_mov_b32 m0, s20
	ds_read_b64_tr_b16 v[180:181], v15 offset:26624
	ds_read_b64_tr_b16 v[182:183], v15 offset:27136
	v_pk_add_f32 v[248:249], v[50:51], v[248:249]
	v_pk_add_f32 v[248:249], v[52:53], v[248:249]
	s_waitcnt lgkmcnt(13)
	v_mfma_f32_32x32x16_bf16 v[96:111], v[156:159], v[120:123], v[96:111]
	v_cvt_pk_bf16_f32 v132, v48, v49
	v_cvt_pk_bf16_f32 v133, v50, v51
	ds_read_b64_tr_b16 v[184:185], v15 offset:30720
	ds_read_b64_tr_b16 v[186:187], v15 offset:31232
	v_pk_add_f32 v[248:249], v[54:55], v[248:249]
	v_pk_add_f32 v[248:249], v[56:57], v[248:249]
	s_waitcnt lgkmcnt(14)
	v_mfma_f32_32x32x16_bf16 v[80:95], v[148:151], v[120:123], v[80:95]
	v_cvt_pk_bf16_f32 v134, v52, v53
	v_cvt_pk_bf16_f32 v135, v54, v55
	ds_read_b64_tr_b16 v[188:189], v15 offset:27648
	ds_read_b64_tr_b16 v[190:191], v15 offset:28160
	s_waitcnt lgkmcnt(14)
	v_mfma_f32_32x32x16_bf16 v[96:111], v[10:13], v[124:127], v[96:111]
	v_pk_add_f32 v[248:249], v[58:59], v[248:249]
	v_pk_add_f32 v[248:249], v[60:61], v[248:249]
	v_cvt_pk_bf16_f32 v128, v56, v57
	v_cvt_pk_bf16_f32 v129, v58, v59
	ds_read_b64_tr_b16 v[10:11], v15 offset:31744
	ds_read_b64_tr_b16 v[12:13], v15 offset:32256
	v_mfma_f32_32x32x16_bf16 v[80:95], v[2:5], v[124:127], v[80:95]
	v_pk_add_f32 v[248:249], v[62:63], v[248:249]
	v_add_f32_e32 v2, v248, v249
	v_cvt_pk_bf16_f32 v130, v60, v61
	v_cvt_pk_bf16_f32 v131, v62, v63
	v_add_u32_e32 v3, 0x15300, v0
	ds_read_b128 v[64:67], v3
	ds_read_b128 v[48:51], v3 offset:128
	ds_read_b128 v[68:71], v3 offset:32
	ds_read_b128 v[52:55], v3 offset:160
	ds_read_b128 v[72:75], v3 offset:64
	ds_read_b128 v[56:59], v3 offset:192
	ds_read_b128 v[76:79], v3 offset:96
	ds_read_b128 v[60:63], v3 offset:224
	s_lshl_b32 s18, 2, s44
	s_and_b32 s18, s18, s81
	s_cmp_lg_u32 s18, 0
	v_add_f32_e32 v225, v14, v2
	s_cselect_b64 s[20:21], -1, 0
	s_cmp_eq_u32 s18, 0
	s_cbranch_scc1 .LBB0_53
	s_add_i32 s18, s33, 0
	s_add_i32 s18, s18, 0x17108
	v_mov_b32_e32 v0, s18
	ds_read_b32 v212, v0
	s_waitcnt lgkmcnt(0)
	v_mul_f32_e32 v225, v225, v212
